# phase-12 epilogue store addresses advanced by constant increments instead of a 64-bit multiply-add per store
# baseline (speedup 1.0000x reference)
; #define PG8_STAGE(bufoff, gbase, voff) do { _Pragma("unroll") for (int _i = 0; _i < 2; ++_i) \
;         __builtin_amdgcn_global_load_lds((const unsigned*)((const char*)(gbase) + (voff)[_i]), (LAS unsigned*)(lds + (bufoff) + ldsw + _i * 8192), 16, 0, 0); } while (0)
; #define PG8_WAIT_V(n) asm volatile("s_waitcnt vmcnt(" #n ")" ::: "memory")
; #define PG8_BAR __builtin_amdgcn_s_barrier()
;     ...
;     const char* cA = (const char*)g.A + (size_t)cur.pm * tstep + (size_t)cur.kt0 * kstep; const char* cB = (const char*)g.Bt + (size_t)cur.e * g.estride + (size_t)cur.pn * tstep + (size_t)cur.kt0 * kstep;
;     PG8_STAGE(PG8_SB(0, 0), cB, voffB); PG8_STAGE(PG8_SB(0, 1), cB + hstep, voffB); PG8_STAGE(PG8_SA(0, 0), cA, voffA); PG8_STAGE(PG8_SA(0, 1), cA + hstep, voffA);
;     if (wr == 1) PG8_BAR;
;     PG8_WAIT_V(2); PG8_BAR;
;     PG8_STAGE(PG8_SB(1, 0), cB + kstep, voffB); PG8_STAGE(PG8_SA(1, 0), cA + kstep, voffA); PG8_STAGE(PG8_SB(1, 1), cB + hstep + kstep, voffB);
;     PG8_WAIT_V(6); PG8_BAR;
.LBB0_4730:
	s_add_u32 s16, s56, 0x4b000000
	s_mov_b64 s[18:19], 0x80
	s_addc_u32 s17, s57, 0
	s_add_i32 m0, s43, 0x18000
	v_lshl_add_u64 v[8:9], v[8:9], 0, s[18:19]
	s_waitcnt vmcnt(2)
	s_barrier
	global_load_lds_dwordx4 v[8:9], off
	v_lshl_add_u64 v[6:7], v[6:7], 0, s[18:19]
	s_add_i32 m0, s43, 0x1a000
	s_add_i32 s58, s43, 0x8000
	global_load_lds_dwordx4 v[6:7], off
	v_lshl_add_u64 v[2:3], v[2:3], 0, s[18:19]
	s_mov_b32 m0, s58
	s_add_i32 s59, s43, 0xa000
	global_load_lds_dwordx4 v[2:3], off
	v_lshl_add_u64 v[2:3], v[4:5], 0, s[18:19]
	s_mov_b32 m0, s59
	s_mov_b64 s[20:21], 0x40080
	global_load_lds_dwordx4 v[2:3], off
	v_lshl_add_u64 v[2:3], v[0:1], 0, s[20:21]
	s_add_i32 m0, s43, 0x1c000
	v_lshl_add_u64 v[4:5], v[2:3], 0, v[128:129]
	global_load_lds_dwordx4 v[4:5], off
	v_lshl_add_u64 v[2:3], v[2:3], 0, v[134:135]
	s_add_i32 m0, s43, 0x1e000
	s_lshl_b32 s3, s3, 5
	global_load_lds_dwordx4 v[2:3], off
	v_lshrrev_b32_e32 v3, 1, v10
	v_and_b32_e32 v3, 24, v3
	v_and_b32_e32 v2, 15, v10
	v_lshlrev_b32_e32 v4, 1, v3
	v_lshl_or_b32 v148, s4, 6, v2
	v_lshl_or_b32 v2, v2, 6, v4
	v_lshlrev_b32_e32 v4, 2, v10
	s_lshl_b32 s4, s4, 13
	v_and_b32_e32 v4, 32, v4
	s_and_b32 s3, s3, 0x60
	v_bitop3_b32 v5, v2, s4, v4 bitop3:0xde
	s_lshl_b32 s4, s3, 7
	v_bitop3_b32 v149, s4, v2, v4 bitop3:0xf6
	v_lshlrev_b32_e32 v2, 14, v12
	v_and_b32_e32 v2, 0xffff8000, v2
	v_or_b32_e32 v150, s3, v3
	v_lshl_add_u32 v2, v13, 11, v2
	v_and_b32_e32 v3, 1, v12
	v_lshl_or_b32 v2, v3, 6, v2
	v_lshl_add_u32 v138, v15, 1, v2
	v_lshlrev_b32_e32 v2, 14, v11
	v_and_b32_e32 v2, 0xffff8000, v2
	s_waitcnt vmcnt(6)
	s_cmpk_lt_u32 s2, 0x100
	v_lshl_add_u32 v2, v14, 11, v2
	v_and_b32_e32 v3, 1, v11
	s_cselect_b64 s[24:25], -1, 0
	v_mov_b32_e32 v139, 0
	v_lshl_or_b32 v2, v3, 6, v2
	s_add_i32 s61, 0, 0x10000
	s_add_i32 s62, 0, 0x14000
	s_ashr_i32 s60, s33, 31
	v_ashrrev_i32_e32 v131, 31, v130
	v_lshl_add_u32 v140, v16, 1, v2
	v_mov_b32_e32 v141, v139
	s_mov_b64 s[26:27], 0x100
	v_add_u32_e32 v151, s61, v149
	v_add_u32_e32 v152, s62, v149
	v_add_u32_e32 v153, 0, v5
	s_mov_b32 s28, 0x3773ad84
	s_mov_b32 s30, 0x3973ad84
	s_mov_b32 s32, 0x4d8d45ca
	s_mov_b32 s63, 0xc3e00000
	s_movk_i32 s64, 0x1c00
	s_mov_b32 s68, 0x1c000
	s_mov_b32 s69, 0
	s_mov_b32 s70, 0x8c000
	s_mov_b32 s71, 0
	v_mov_b32_e32 v154, 0x43e00000
	global_load_dwordx4 v[230:233], v139, s[10:11]
	global_load_dwordx3 v[234:236], v139, s[10:11] offset:16
	s_waitcnt vmcnt(0)
	s_barrier
	s_branch .LBB0_4733

;     __device__ __forceinline__ float qscale(const Unit& u) const { return ((u.pn >= 8 && u.pn <= 11) || u.pn == 17) ? 0.5f : 1.0f; }
; __device__ __forceinline__ void ln_stats(const float* st, int row, float& mu, float& rs) { const f32x2 s = *(const f32x2*)(st + 2 * (size_t)row); mu = s[0] * (1.0f / DM); rs = 1.0f / sqrtf(s[1] * (1.0f / DM) - mu * mu + LN_EPS); }
;     ...
;         if constexpr (QM == 2) { const float qs0_ = g.qs * E.qscale(cur), qs1_ = qs0_ * g.qs_b1; _Pragma("unroll") for (int a = 0; a < 2; ++a) _Pragma("unroll") for (int b = 0; b < 2; ++b) _Pragma("unroll") for (int m = 0; m < 4; ++m) _Pragma("unroll") for (int n = 0; n < 2; ++n) { const v4i t_ = __builtin_bit_cast(v4i, acc[a][b][m][n]); acc[a][b][m][n] = (f32x4){(float)t_[0], (float)t_[1], (float)t_[2], (float)t_[3]} * (b == 0 ? qs0_ : qs1_); } }
;     __device__ __forceinline__ void operator()(EPI_ARGS) const {
;     ...
;             for (int m = 0; m < 4; ++m) { const int row = row0 + ai * HALF + m * 16; f32x4 r[2];
;                 float mu = 0.f, rs = 1.f; if constexpr (FOLD) ln_stats(st, row, mu, rs);
; #pragma unroll
;                 for (int n = 0; n < 2; ++n) { f32x4 g = acc[ai][0][m][n], up = acc[ai][1][m][n];
;                     if constexpr (!PRE) { g = g * ascale; up = up * ascale; }
;                     if constexpr (FOLD) { g = (g - cg[n] * mu) * rs + dg[n]; up = (up - cu[n] * mu) * rs + du[n]; }
;                     if constexpr (!PRE) up = up * oscale;
; #pragma unroll
;                     for (int j = 0; j < 4; ++j) { const float e = __builtin_amdgcn_exp2f(g[j] * -1.4426950408889634f); r[n][j] = g[j] * __builtin_amdgcn_rcpf(1.0f + e) * up[j]; } }
.LBB0_4741:
	v_cvt_f32_i32_e32 v121, v121
	v_cvt_f32_i32_e32 v123, v123
	v_cvt_f32_i32_e32 v122, v122
	v_cvt_f32_i32_e32 v120, v120
	v_cvt_f32_i32_e32 v125, v125
	v_cvt_f32_i32_e32 v124, v124
	v_cvt_f32_i32_e32 v113, v113
	v_cvt_f32_i32_e32 v115, v115
	v_cvt_f32_i32_e32 v114, v114
	v_cvt_f32_i32_e32 v112, v112
	v_cvt_f32_i32_e32 v127, v127
	v_cvt_f32_i32_e32 v126, v126
	v_cvt_f32_i32_e32 v117, v117
	v_cvt_f32_i32_e32 v116, v116
	v_cvt_f32_i32_e32 v105, v105
	v_cvt_f32_i32_e32 v107, v107
	v_cvt_f32_i32_e32 v106, v106
	v_cvt_f32_i32_e32 v104, v104
	v_cvt_f32_i32_e32 v119, v119
	v_cvt_f32_i32_e32 v118, v118
	v_cvt_f32_i32_e32 v109, v109
	v_cvt_f32_i32_e32 v108, v108
	v_cvt_f32_i32_e32 v97, v97
	v_cvt_f32_i32_e32 v99, v99
	v_cvt_f32_i32_e32 v98, v98
	v_cvt_f32_i32_e32 v96, v96
	v_cvt_f32_i32_e32 v93, v93
	v_cvt_f32_i32_e32 v92, v92
	v_cvt_f32_i32_e32 v91, v91
	v_cvt_f32_i32_e32 v90, v90
	v_cvt_f32_i32_e32 v85, v85
	v_cvt_f32_i32_e32 v84, v84
	v_cvt_f32_i32_e32 v83, v83
	v_cvt_f32_i32_e32 v82, v82
	v_cvt_f32_i32_e32 v77, v77
	v_cvt_f32_i32_e32 v76, v76
	v_cvt_f32_i32_e32 v75, v75
	v_cvt_f32_i32_e32 v74, v74
	v_cvt_f32_i32_e32 v111, v111
	v_cvt_f32_i32_e32 v110, v110
	v_cvt_f32_i32_e32 v101, v101
	v_cvt_f32_i32_e32 v100, v100
	v_cvt_f32_i32_e32 v95, v95
	v_cvt_f32_i32_e32 v94, v94
	v_cvt_f32_i32_e32 v89, v89
	v_cvt_f32_i32_e32 v88, v88
	v_cvt_f32_i32_e32 v87, v87
	v_cvt_f32_i32_e32 v86, v86
	v_cvt_f32_i32_e32 v81, v81
	v_cvt_f32_i32_e32 v80, v80
	v_cvt_f32_i32_e32 v79, v79
	v_cvt_f32_i32_e32 v78, v78
	v_cvt_f32_i32_e32 v73, v73
	v_cvt_f32_i32_e32 v72, v72
	v_cvt_f32_i32_e32 v65, v65
	v_cvt_f32_i32_e32 v67, v67
	v_cvt_f32_i32_e32 v66, v66
	v_cvt_f32_i32_e32 v64, v64
	v_cvt_f32_i32_e32 v103, v103
	v_cvt_f32_i32_e32 v102, v102
	v_cvt_f32_i32_e32 v69, v69
	v_cvt_f32_i32_e32 v68, v68
	v_cvt_f32_i32_e32 v57, v57
	v_cvt_f32_i32_e32 v59, v59
	v_cvt_f32_i32_e32 v58, v58
	v_cvt_f32_i32_e32 v56, v56
	v_cvt_f32_i32_e32 v71, v71
	v_cvt_f32_i32_e32 v70, v70
	v_cvt_f32_i32_e32 v61, v61
	v_cvt_f32_i32_e32 v60, v60
	v_cvt_f32_i32_e32 v49, v49
	v_cvt_f32_i32_e32 v51, v51
	v_cvt_f32_i32_e32 v50, v50
	v_cvt_f32_i32_e32 v48, v48
	v_cvt_f32_i32_e32 v63, v63
	v_cvt_f32_i32_e32 v62, v62
	v_cvt_f32_i32_e32 v53, v53
	v_cvt_f32_i32_e32 v52, v52
	v_cvt_f32_i32_e32 v41, v41
	v_cvt_f32_i32_e32 v43, v43
	v_cvt_f32_i32_e32 v42, v42
	v_cvt_f32_i32_e32 v40, v40
	v_cvt_f32_i32_e32 v55, v55
	v_cvt_f32_i32_e32 v54, v54
	v_cvt_f32_i32_e32 v45, v45
	v_cvt_f32_i32_e32 v44, v44
	v_cvt_f32_i32_e32 v33, v33
	v_cvt_f32_i32_e32 v35, v35
	v_cvt_f32_i32_e32 v34, v34
	v_cvt_f32_i32_e32 v32, v32
	v_cvt_f32_i32_e32 v29, v29
	v_cvt_f32_i32_e32 v28, v28
	v_cvt_f32_i32_e32 v27, v27
	v_cvt_f32_i32_e32 v26, v26
	v_cvt_f32_i32_e32 v21, v21
	v_cvt_f32_i32_e32 v20, v20
	v_cvt_f32_i32_e32 v19, v19
	v_cvt_f32_i32_e32 v18, v18
	v_cvt_f32_i32_e32 v13, v13
	v_cvt_f32_i32_e32 v12, v12
	v_cvt_f32_i32_e32 v9, v9
	v_cvt_f32_i32_e32 v8, v8
	v_cvt_f32_i32_e32 v5, v5
	v_cvt_f32_i32_e32 v4, v4
	v_cvt_f32_i32_e32 v1, v1
	v_cvt_f32_i32_e32 v0, v0
	v_cvt_f32_i32_e32 v47, v47
	v_cvt_f32_i32_e32 v46, v46
	v_cvt_f32_i32_e32 v37, v37
	v_cvt_f32_i32_e32 v36, v36
	v_cvt_f32_i32_e32 v31, v31
	v_cvt_f32_i32_e32 v30, v30
	v_cvt_f32_i32_e32 v25, v25
	v_cvt_f32_i32_e32 v24, v24
	v_cvt_f32_i32_e32 v23, v23
	v_cvt_f32_i32_e32 v22, v22
	v_cvt_f32_i32_e32 v17, v17
	v_cvt_f32_i32_e32 v16, v16
	v_cvt_f32_i32_e32 v15, v15
	v_cvt_f32_i32_e32 v14, v14
	v_mul_f32_e32 v146, 0xb7afc6c0, v124
	v_exp_f32_e32 v147, v146
	v_mul_f32_e32 v146, 0xb7afc6c0, v125
	v_cvt_f32_i32_e32 v39, v39
	v_cvt_f32_i32_e32 v38, v38
	v_exp_f32_e32 v144, v146
	v_fma_f32 v147, v147, s32, s32
	v_rcp_f32_e32 v145, v147
	v_fma_f32 v147, v144, s32, s32
	v_rcp_f32_e32 v144, v147
	v_mul_f32_e32 v145, v124, v145
	v_mul_f32_e32 v124, 0xb7afc6c0, v126
	v_exp_f32_e32 v124, v124
	v_mul_f32_e32 v144, v125, v144
	v_mul_f32_e32 v125, 0xb7afc6c0, v127
	v_exp_f32_e32 v125, v125
	v_mul_f32_e32 v145, v92, v145
	v_fma_f32 v124, v124, s32, s32
	v_mul_f32_e32 v92, 0xb7afc6c0, v120
	v_rcp_f32_e32 v124, v124
	v_fma_f32 v125, v125, s32, s32
	v_exp_f32_e32 v92, v92
	v_rcp_f32_e32 v125, v125
	v_mul_f32_e32 v126, v126, v124
	v_mul_f32_e32 v144, v93, v144
	v_fma_f32 v124, v92, s32, s32
	v_mul_f32_e32 v127, v127, v125
	v_rcp_f32_e32 v124, v124
	v_mul_f32_e32 v125, 0xb7afc6c0, v121
	v_exp_f32_e32 v125, v125
	v_med3_f32 v145, v145, s63, v154
	v_mul_f32_e32 v120, v120, v124
	v_mul_f32_e32 v88, v88, v120
	v_fma_f32 v120, v125, s32, s32
	v_mul_f32_e32 v124, 0xb7afc6c0, v122
	v_rcp_f32_e32 v120, v120
	v_exp_f32_e32 v124, v124
	v_mul_f32_e32 v125, 0xb7afc6c0, v123
	v_exp_f32_e32 v125, v125
	v_mul_f32_e32 v120, v121, v120
	v_fma_f32 v121, v124, s32, s32
	v_rcp_f32_e32 v121, v121
	v_fma_f32 v124, v125, s32, s32
	v_rcp_f32_e32 v124, v124
	v_med3_f32 v144, v144, s63, v154
	v_mul_f32_e32 v122, v122, v121
	v_mul_f32_e32 v122, v90, v122
	v_mul_f32_e32 v90, v123, v124
	v_mul_f32_e32 v123, v91, v90
	v_cvt_pk_fp8_f32 v90, v145, v144
	v_mul_f32_e32 v89, v89, v120
	v_mul_f32_e32 v126, v94, v126
	v_mul_f32_e32 v127, v95, v127
	v_med3_f32 v88, v88, s63, v154
	v_med3_f32 v89, v89, s63, v154
	v_med3_f32 v144, v126, s63, v154
	v_med3_f32 v145, v127, s63, v154
	v_cvt_pk_fp8_f32 v91, v88, v89
	v_cvt_pk_fp8_f32 v90, v144, v145 op_sel:[0,0,1]
	v_med3_f32 v144, v122, s63, v154
	v_mul_f32_e32 v122, 0xb7afc6c0, v116
	v_med3_f32 v145, v123, s63, v154
	v_exp_f32_e32 v122, v122
	v_mul_f32_e32 v123, 0xb7afc6c0, v117
	v_exp_f32_e32 v123, v123
	v_cvt_pk_fp8_f32 v91, v144, v145 op_sel:[0,0,1]
	v_lshl_add_u32 v156, s44, 8, v148
	v_lshl_or_b32 v146, s42, 7, v150
	v_mov_b64_e32 v[144:145], s[16:17]
	v_ashrrev_i32_e32 v147, 31, v146
; __device__ __forceinline__ u32x4 pack8bf(const f32x4 a, const f32x4 b) { u32x4 w; w.x = cvt_pk_bf16(a[0], a[1]); w.y = cvt_pk_bf16(a[2], a[3]); w.z = cvt_pk_bf16(b[0], b[1]); w.w = cvt_pk_bf16(b[2], b[3]); return w; }
; __device__ __forceinline__ void ln_stats(const float* st, int row, float& mu, float& rs) { const f32x2 s = *(const f32x2*)(st + 2 * (size_t)row); mu = s[0] * (1.0f / DM); rs = 1.0f / sqrtf(s[1] * (1.0f / DM) - mu * mu + LN_EPS); }
;     __device__ __forceinline__ void operator()(EPI_ARGS) const {
;     ...
;             for (int m = 0; m < 4; ++m) { const int row = row0 + ai * HALF + m * 16; f32x4 r[2];
;                 float mu = 0.f, rs = 1.f; if constexpr (FOLD) ln_stats(st, row, mu, rs);
; #pragma unroll
;                 for (int n = 0; n < 2; ++n) { f32x4 g = acc[ai][0][m][n], up = acc[ai][1][m][n];
;                     if constexpr (!PRE) { g = g * ascale; up = up * ascale; }
;                     if constexpr (FOLD) { g = (g - cg[n] * mu) * rs + dg[n]; up = (up - cu[n] * mu) * rs + du[n]; }
;                     if constexpr (!PRE) up = up * oscale;
; #pragma unroll
;                     for (int j = 0; j < 4; ++j) { const float e = __builtin_amdgcn_exp2f(g[j] * -1.4426950408889634f); r[n][j] = g[j] * __builtin_amdgcn_rcpf(1.0f + e) * up[j]; } }
;                 if constexpr (F8OUT) *(u32x2*)((unsigned char*)O + (size_t)row * ldc + col0) = pack8fp8(r[0], r[1]);
;                 else *(u32x4*)((bf16_t*)O + (size_t)row * ldc + col0) = pack8bf(r[0], r[1]); }
	v_mad_i64_i32 v[88:89], s[4:5], v156, s64, v[144:145]
	v_fma_f32 v122, v122, s32, s32
	v_lshl_add_u64 v[250:251], v[88:89], 0, v[146:147]
	v_rcp_f32_e32 v122, v122
	v_fma_f32 v123, v123, s32, s32
	v_rcp_f32_e32 v123, v123
	global_store_dwordx2 v[250:251], v[90:91], off
	v_mul_f32_e32 v91, 0xb7afc6c0, v118
	v_exp_f32_e32 v91, v91
	v_mul_f32_e32 v88, 0xb7afc6c0, v119
	v_exp_f32_e32 v88, v88
	v_mul_f32_e32 v90, v116, v122
	v_mul_f32_e32 v84, v84, v90
	v_mul_f32_e32 v90, v117, v123
	v_mul_f32_e32 v85, v85, v90
	v_fma_f32 v90, v91, s32, s32
	v_rcp_f32_e32 v90, v90
	v_fma_f32 v91, v88, s32, s32
	v_mul_f32_e32 v88, 0xb7afc6c0, v112
	v_rcp_f32_e32 v91, v91
	v_exp_f32_e32 v88, v88
	v_mul_f32_e32 v90, v118, v90
	v_mul_f32_e32 v86, v86, v90
	v_mul_f32_e32 v90, v119, v91
	v_fma_f32 v91, v88, s32, s32
	v_rcp_f32_e32 v91, v91
	v_mul_f32_e32 v88, 0xb7afc6c0, v113
	v_exp_f32_e32 v88, v88
	v_mul_f32_e32 v87, v87, v90
	v_mul_f32_e32 v90, v112, v91
	v_mul_f32_e32 v91, 0xb7afc6c0, v114
	v_mul_f32_e32 v80, v80, v90
	v_fma_f32 v90, v88, s32, s32
	v_exp_f32_e32 v91, v91
	v_mul_f32_e32 v88, 0xb7afc6c0, v115
	v_exp_f32_e32 v88, v88
	v_rcp_f32_e32 v90, v90
	v_fma_f32 v91, v91, s32, s32
	v_rcp_f32_e32 v91, v91
	v_fma_f32 v88, v88, s32, s32
	v_rcp_f32_e32 v88, v88
	v_mul_f32_e32 v90, v113, v90
	v_mul_f32_e32 v81, v81, v90
	v_mul_f32_e32 v90, v114, v91
	v_mul_f32_e32 v90, v82, v90
	v_mul_f32_e32 v82, v115, v88
	v_mul_f32_e32 v91, v83, v82
	v_med3_f32 v83, v84, s63, v154
	v_med3_f32 v84, v85, s63, v154
	v_cvt_pk_fp8_f32 v82, v83, v84
	v_med3_f32 v80, v80, s63, v154
	v_med3_f32 v81, v81, s63, v154
	v_med3_f32 v86, v86, s63, v154
	v_med3_f32 v87, v87, s63, v154
	v_cvt_pk_fp8_f32 v83, v80, v81
	v_cvt_pk_fp8_f32 v82, v86, v87 op_sel:[0,0,1]
	v_mul_f32_e32 v86, 0xb7afc6c0, v108
	v_exp_f32_e32 v86, v86
	v_mul_f32_e32 v87, 0xb7afc6c0, v109
	v_med3_f32 v80, v90, s63, v154
	v_med3_f32 v81, v91, s63, v154
	v_exp_f32_e32 v87, v87
	v_cvt_pk_fp8_f32 v83, v80, v81 op_sel:[0,0,1]
	v_fma_f32 v86, v86, s32, s32
	v_lshl_add_u64 v[250:251], v[250:251], 0, s[68:69]
	v_rcp_f32_e32 v86, v86
	v_fma_f32 v87, v87, s32, s32
	v_rcp_f32_e32 v87, v87
	global_store_dwordx2 v[250:251], v[82:83], off
	v_mul_f32_e32 v83, 0xb7afc6c0, v110
	v_exp_f32_e32 v83, v83
	v_mul_f32_e32 v80, 0xb7afc6c0, v111
	v_exp_f32_e32 v80, v80
	v_mul_f32_e32 v82, v108, v86
	v_mul_f32_e32 v76, v76, v82
	v_mul_f32_e32 v82, v109, v87
	v_mul_f32_e32 v77, v77, v82
	v_fma_f32 v82, v83, s32, s32
	v_rcp_f32_e32 v82, v82
	v_fma_f32 v83, v80, s32, s32
	v_mul_f32_e32 v80, 0xb7afc6c0, v104
	v_rcp_f32_e32 v83, v83
	v_exp_f32_e32 v80, v80
	v_mul_f32_e32 v82, v110, v82
	v_mul_f32_e32 v78, v78, v82
	v_mul_f32_e32 v82, v111, v83
	v_fma_f32 v83, v80, s32, s32
	v_rcp_f32_e32 v83, v83
	v_mul_f32_e32 v80, 0xb7afc6c0, v105
	v_exp_f32_e32 v80, v80
	v_mul_f32_e32 v79, v79, v82
	v_mul_f32_e32 v82, v104, v83
	v_mul_f32_e32 v83, 0xb7afc6c0, v106
	v_mul_f32_e32 v72, v72, v82
	v_fma_f32 v82, v80, s32, s32
	v_exp_f32_e32 v83, v83
	v_mul_f32_e32 v80, 0xb7afc6c0, v107
	v_exp_f32_e32 v80, v80
	v_rcp_f32_e32 v82, v82
	v_fma_f32 v83, v83, s32, s32
	v_rcp_f32_e32 v83, v83
	v_fma_f32 v80, v80, s32, s32
	v_rcp_f32_e32 v80, v80
	v_mul_f32_e32 v82, v105, v82
	v_mul_f32_e32 v73, v73, v82
	v_mul_f32_e32 v82, v106, v83
	v_mul_f32_e32 v82, v74, v82
	v_mul_f32_e32 v74, v107, v80
	v_mul_f32_e32 v83, v75, v74
	v_med3_f32 v75, v76, s63, v154
	v_med3_f32 v76, v77, s63, v154
	v_cvt_pk_fp8_f32 v74, v75, v76
	v_med3_f32 v72, v72, s63, v154
	v_med3_f32 v73, v73, s63, v154
	v_med3_f32 v78, v78, s63, v154
	v_med3_f32 v79, v79, s63, v154
	v_cvt_pk_fp8_f32 v75, v72, v73
	v_cvt_pk_fp8_f32 v74, v78, v79 op_sel:[0,0,1]
	v_mul_f32_e32 v78, 0xb7afc6c0, v100
	v_exp_f32_e32 v78, v78
	v_mul_f32_e32 v79, 0xb7afc6c0, v101
	v_med3_f32 v72, v82, s63, v154
	v_med3_f32 v73, v83, s63, v154
	v_exp_f32_e32 v79, v79
	v_cvt_pk_fp8_f32 v75, v72, v73 op_sel:[0,0,1]
	v_fma_f32 v78, v78, s32, s32
	v_lshl_add_u64 v[250:251], v[250:251], 0, s[68:69]
	v_rcp_f32_e32 v78, v78
	v_fma_f32 v79, v79, s32, s32
	v_rcp_f32_e32 v79, v79
	global_store_dwordx2 v[250:251], v[74:75], off
	v_mul_f32_e32 v75, 0xb7afc6c0, v102
	v_exp_f32_e32 v75, v75
	v_mul_f32_e32 v72, 0xb7afc6c0, v103
	v_exp_f32_e32 v72, v72
	v_mul_f32_e32 v74, v100, v78
	v_mul_f32_e32 v68, v68, v74
	v_mul_f32_e32 v74, v101, v79
	v_mul_f32_e32 v69, v69, v74
	v_fma_f32 v74, v75, s32, s32
	v_rcp_f32_e32 v74, v74
	v_fma_f32 v75, v72, s32, s32
	v_mul_f32_e32 v72, 0xb7afc6c0, v96
	v_rcp_f32_e32 v75, v75
	v_exp_f32_e32 v72, v72
	v_mul_f32_e32 v74, v102, v74
	v_mul_f32_e32 v70, v70, v74
	v_mul_f32_e32 v74, v103, v75
	v_fma_f32 v75, v72, s32, s32
	v_rcp_f32_e32 v75, v75
	v_mul_f32_e32 v72, 0xb7afc6c0, v97
	v_exp_f32_e32 v72, v72
	v_mul_f32_e32 v71, v71, v74
	v_mul_f32_e32 v74, v96, v75
	v_mul_f32_e32 v75, 0xb7afc6c0, v98
	v_mul_f32_e32 v64, v64, v74
	v_fma_f32 v74, v72, s32, s32
	v_exp_f32_e32 v75, v75
	v_mul_f32_e32 v72, 0xb7afc6c0, v99
	v_exp_f32_e32 v72, v72
	v_rcp_f32_e32 v74, v74
	v_fma_f32 v75, v75, s32, s32
	v_rcp_f32_e32 v75, v75
	v_fma_f32 v72, v72, s32, s32
	v_rcp_f32_e32 v72, v72
	v_mul_f32_e32 v74, v97, v74
	v_mul_f32_e32 v65, v65, v74
	v_mul_f32_e32 v74, v98, v75
	v_mul_f32_e32 v74, v66, v74
	v_mul_f32_e32 v66, v99, v72
	v_mul_f32_e32 v75, v67, v66
	v_med3_f32 v67, v68, s63, v154
	v_med3_f32 v68, v69, s63, v154
	v_cvt_pk_fp8_f32 v66, v67, v68
	v_med3_f32 v64, v64, s63, v154
	v_med3_f32 v65, v65, s63, v154
	v_cvt_pk_fp8_f32 v67, v64, v65
	v_med3_f32 v70, v70, s63, v154
	v_med3_f32 v71, v71, s63, v154
	v_cvt_pk_fp8_f32 v66, v70, v71 op_sel:[0,0,1]
	v_med3_f32 v64, v74, s63, v154
	v_med3_f32 v65, v75, s63, v154
	v_mul_f32_e32 v70, 0xb7afc6c0, v60
; __device__ __forceinline__ u32x4 pack8bf(const f32x4 a, const f32x4 b) { u32x4 w; w.x = cvt_pk_bf16(a[0], a[1]); w.y = cvt_pk_bf16(a[2], a[3]); w.z = cvt_pk_bf16(b[0], b[1]); w.w = cvt_pk_bf16(b[2], b[3]); return w; }
; __device__ __forceinline__ void ln_stats(const float* st, int row, float& mu, float& rs) { const f32x2 s = *(const f32x2*)(st + 2 * (size_t)row); mu = s[0] * (1.0f / DM); rs = 1.0f / sqrtf(s[1] * (1.0f / DM) - mu * mu + LN_EPS); }
;     __device__ __forceinline__ void operator()(EPI_ARGS) const {
;     ...
;             for (int m = 0; m < 4; ++m) { const int row = row0 + ai * HALF + m * 16; f32x4 r[2];
;                 float mu = 0.f, rs = 1.f; if constexpr (FOLD) ln_stats(st, row, mu, rs);
; #pragma unroll
;                 for (int n = 0; n < 2; ++n) { f32x4 g = acc[ai][0][m][n], up = acc[ai][1][m][n];
;                     if constexpr (!PRE) { g = g * ascale; up = up * ascale; }
;                     if constexpr (FOLD) { g = (g - cg[n] * mu) * rs + dg[n]; up = (up - cu[n] * mu) * rs + du[n]; }
;                     if constexpr (!PRE) up = up * oscale;
; #pragma unroll
;                     for (int j = 0; j < 4; ++j) { const float e = __builtin_amdgcn_exp2f(g[j] * -1.4426950408889634f); r[n][j] = g[j] * __builtin_amdgcn_rcpf(1.0f + e) * up[j]; } }
;                 if constexpr (F8OUT) *(u32x2*)((unsigned char*)O + (size_t)row * ldc + col0) = pack8fp8(r[0], r[1]);
;                 else *(u32x4*)((bf16_t*)O + (size_t)row * ldc + col0) = pack8bf(r[0], r[1]); }
	v_cvt_pk_fp8_f32 v67, v64, v65 op_sel:[0,0,1]
	v_exp_f32_e32 v70, v70
	v_mul_f32_e32 v71, 0xb7afc6c0, v61
	v_exp_f32_e32 v71, v71
	v_lshl_add_u64 v[250:251], v[250:251], 0, s[68:69]
	global_store_dwordx2 v[250:251], v[66:67], off
	v_fma_f32 v66, v70, s32, s32
	v_rcp_f32_e32 v66, v66
	v_fma_f32 v67, v71, s32, s32
	v_rcp_f32_e32 v67, v67
	v_mul_f32_e32 v60, v60, v66
	v_mul_f32_e32 v66, 0xb7afc6c0, v62
	v_mul_f32_e32 v61, v61, v67
	v_exp_f32_e32 v66, v66
	v_mul_f32_e32 v67, 0xb7afc6c0, v63
	v_exp_f32_e32 v67, v67
	v_mul_f32_e32 v65, 0xb7afc6c0, v56
	v_fma_f32 v66, v66, s32, s32
	v_rcp_f32_e32 v66, v66
	v_fma_f32 v67, v67, s32, s32
	v_exp_f32_e32 v65, v65
	v_rcp_f32_e32 v67, v67
	v_mul_f32_e32 v62, v62, v66
	v_mul_f32_e32 v60, v28, v60
	v_fma_f32 v66, v65, s32, s32
	v_mul_f32_e32 v63, v63, v67
	v_rcp_f32_e32 v66, v66
	v_mul_f32_e32 v67, 0xb7afc6c0, v57
	v_exp_f32_e32 v67, v67
	v_mul_f32_e32 v61, v29, v61
	v_mul_f32_e32 v56, v56, v66
	v_mul_f32_e32 v24, v24, v56
	v_fma_f32 v56, v67, s32, s32
	v_mul_f32_e32 v66, 0xb7afc6c0, v58
	v_rcp_f32_e32 v56, v56
	v_exp_f32_e32 v66, v66
	v_mul_f32_e32 v67, 0xb7afc6c0, v59
	v_exp_f32_e32 v67, v67
	v_mul_f32_e32 v56, v57, v56
	v_fma_f32 v57, v66, s32, s32
	v_rcp_f32_e32 v57, v57
	v_fma_f32 v66, v67, s32, s32
	v_rcp_f32_e32 v66, v66
	v_mul_f32_e32 v25, v25, v56
	v_mul_f32_e32 v58, v58, v57
	v_mul_f32_e32 v58, v26, v58
	v_mul_f32_e32 v26, v59, v66
	v_mul_f32_e32 v59, v27, v26
	v_med3_f32 v27, v60, s63, v154
	v_med3_f32 v56, v61, s63, v154
	v_cvt_pk_fp8_f32 v26, v27, v56
	v_med3_f32 v24, v24, s63, v154
	v_med3_f32 v25, v25, s63, v154
	v_cvt_pk_fp8_f32 v27, v24, v25
	v_med3_f32 v24, v58, s63, v154
	v_mul_f32_e32 v58, 0xb7afc6c0, v52
	v_mul_f32_e32 v62, v30, v62
	v_mul_f32_e32 v63, v31, v63
	v_med3_f32 v25, v59, s63, v154
	v_exp_f32_e32 v58, v58
	v_mul_f32_e32 v59, 0xb7afc6c0, v53
	v_med3_f32 v56, v62, s63, v154
	v_med3_f32 v57, v63, s63, v154
	v_exp_f32_e32 v59, v59
	v_cvt_pk_fp8_f32 v26, v56, v57 op_sel:[0,0,1]
	v_cvt_pk_fp8_f32 v27, v24, v25 op_sel:[0,0,1]
	v_fma_f32 v58, v58, s32, s32
	v_lshl_add_u64 v[250:251], v[250:251], 0, s[70:71]
	v_rcp_f32_e32 v58, v58
	v_fma_f32 v59, v59, s32, s32
	v_rcp_f32_e32 v59, v59
	global_store_dwordx2 v[250:251], v[26:27], off
	v_mul_f32_e32 v27, 0xb7afc6c0, v54
	v_exp_f32_e32 v27, v27
	v_mul_f32_e32 v24, 0xb7afc6c0, v55
	v_exp_f32_e32 v24, v24
	v_mul_f32_e32 v26, v52, v58
	v_mul_f32_e32 v20, v20, v26
	v_mul_f32_e32 v26, v53, v59
	v_mul_f32_e32 v21, v21, v26
	v_fma_f32 v26, v27, s32, s32
	v_rcp_f32_e32 v26, v26
	v_fma_f32 v27, v24, s32, s32
	v_mul_f32_e32 v24, 0xb7afc6c0, v48
	v_rcp_f32_e32 v27, v27
	v_exp_f32_e32 v24, v24
	v_mul_f32_e32 v26, v54, v26
	v_mul_f32_e32 v22, v22, v26
	v_mul_f32_e32 v26, v55, v27
	v_fma_f32 v27, v24, s32, s32
	v_rcp_f32_e32 v27, v27
	v_mul_f32_e32 v24, 0xb7afc6c0, v49
	v_exp_f32_e32 v24, v24
	v_mul_f32_e32 v23, v23, v26
	v_mul_f32_e32 v26, v48, v27
	v_mul_f32_e32 v27, 0xb7afc6c0, v50
	v_mul_f32_e32 v16, v16, v26
	v_fma_f32 v26, v24, s32, s32
	v_exp_f32_e32 v27, v27
	v_mul_f32_e32 v24, 0xb7afc6c0, v51
	v_exp_f32_e32 v24, v24
	v_rcp_f32_e32 v26, v26
	v_fma_f32 v27, v27, s32, s32
	v_rcp_f32_e32 v27, v27
	v_fma_f32 v24, v24, s32, s32
	v_rcp_f32_e32 v24, v24
	v_mul_f32_e32 v26, v49, v26
	v_mul_f32_e32 v17, v17, v26
	v_mul_f32_e32 v26, v50, v27
	v_mul_f32_e32 v26, v18, v26
	v_mul_f32_e32 v18, v51, v24
	v_mul_f32_e32 v27, v19, v18
	v_med3_f32 v19, v20, s63, v154
	v_med3_f32 v20, v21, s63, v154
	v_cvt_pk_fp8_f32 v18, v19, v20
	v_med3_f32 v16, v16, s63, v154
	v_med3_f32 v17, v17, s63, v154
	v_med3_f32 v22, v22, s63, v154
	v_med3_f32 v23, v23, s63, v154
	v_cvt_pk_fp8_f32 v19, v16, v17
	v_cvt_pk_fp8_f32 v18, v22, v23 op_sel:[0,0,1]
	v_mul_f32_e32 v22, 0xb7afc6c0, v44
	v_exp_f32_e32 v22, v22
	v_mul_f32_e32 v23, 0xb7afc6c0, v45
	v_med3_f32 v16, v26, s63, v154
	v_med3_f32 v17, v27, s63, v154
	v_exp_f32_e32 v23, v23
	v_cvt_pk_fp8_f32 v19, v16, v17 op_sel:[0,0,1]
	v_fma_f32 v22, v22, s32, s32
; __device__ __forceinline__ u32x4 pack8bf(const f32x4 a, const f32x4 b) { u32x4 w; w.x = cvt_pk_bf16(a[0], a[1]); w.y = cvt_pk_bf16(a[2], a[3]); w.z = cvt_pk_bf16(b[0], b[1]); w.w = cvt_pk_bf16(b[2], b[3]); return w; }
; __device__ __forceinline__ void ln_stats(const float* st, int row, float& mu, float& rs) { const f32x2 s = *(const f32x2*)(st + 2 * (size_t)row); mu = s[0] * (1.0f / DM); rs = 1.0f / sqrtf(s[1] * (1.0f / DM) - mu * mu + LN_EPS); }
;     __device__ __forceinline__ void operator()(EPI_ARGS) const {
;     ...
;             for (int m = 0; m < 4; ++m) { const int row = row0 + ai * HALF + m * 16; f32x4 r[2];
;                 float mu = 0.f, rs = 1.f; if constexpr (FOLD) ln_stats(st, row, mu, rs);
; #pragma unroll
;                 for (int n = 0; n < 2; ++n) { f32x4 g = acc[ai][0][m][n], up = acc[ai][1][m][n];
;                     if constexpr (!PRE) { g = g * ascale; up = up * ascale; }
;                     if constexpr (FOLD) { g = (g - cg[n] * mu) * rs + dg[n]; up = (up - cu[n] * mu) * rs + du[n]; }
;                     if constexpr (!PRE) up = up * oscale;
; #pragma unroll
;                     for (int j = 0; j < 4; ++j) { const float e = __builtin_amdgcn_exp2f(g[j] * -1.4426950408889634f); r[n][j] = g[j] * __builtin_amdgcn_rcpf(1.0f + e) * up[j]; } }
;                 if constexpr (F8OUT) *(u32x2*)((unsigned char*)O + (size_t)row * ldc + col0) = pack8fp8(r[0], r[1]);
;                 else *(u32x4*)((bf16_t*)O + (size_t)row * ldc + col0) = pack8bf(r[0], r[1]); }
	v_lshl_add_u64 v[250:251], v[250:251], 0, s[68:69]
	v_rcp_f32_e32 v22, v22
	v_fma_f32 v23, v23, s32, s32
	v_rcp_f32_e32 v23, v23
	global_store_dwordx2 v[250:251], v[18:19], off
	v_mul_f32_e32 v19, 0xb7afc6c0, v46
	v_exp_f32_e32 v19, v19
	v_mul_f32_e32 v16, 0xb7afc6c0, v47
	v_exp_f32_e32 v16, v16
	v_mul_f32_e32 v18, v44, v22
	v_mul_f32_e32 v12, v12, v18
	v_mul_f32_e32 v18, v45, v23
	v_mul_f32_e32 v13, v13, v18
	v_fma_f32 v18, v19, s32, s32
	v_rcp_f32_e32 v18, v18
	v_fma_f32 v19, v16, s32, s32
	v_mul_f32_e32 v16, 0xb7afc6c0, v40
	v_rcp_f32_e32 v19, v19
	v_exp_f32_e32 v16, v16
	v_mul_f32_e32 v18, v46, v18
	v_mul_f32_e32 v14, v14, v18
	v_mul_f32_e32 v18, v47, v19
	v_fma_f32 v19, v16, s32, s32
	v_rcp_f32_e32 v19, v19
	v_mul_f32_e32 v16, 0xb7afc6c0, v41
	v_exp_f32_e32 v16, v16
	v_mul_f32_e32 v15, v15, v18
	v_mul_f32_e32 v18, v40, v19
	v_mul_f32_e32 v19, 0xb7afc6c0, v42
	v_mul_f32_e32 v8, v8, v18
	v_fma_f32 v18, v16, s32, s32
	v_exp_f32_e32 v19, v19
	v_mul_f32_e32 v16, 0xb7afc6c0, v43
	v_exp_f32_e32 v16, v16
	v_rcp_f32_e32 v18, v18
	v_fma_f32 v19, v19, s32, s32
	v_cvt_f32_i32_e32 v11, v11
	v_cvt_f32_i32_e32 v10, v10
	v_rcp_f32_e32 v19, v19
	v_fma_f32 v16, v16, s32, s32
	v_rcp_f32_e32 v16, v16
	v_mul_f32_e32 v18, v41, v18
	v_mul_f32_e32 v9, v9, v18
	v_mul_f32_e32 v18, v42, v19
	v_mul_f32_e32 v18, v10, v18
	v_mul_f32_e32 v10, v43, v16
	v_mul_f32_e32 v19, v11, v10
	v_med3_f32 v11, v12, s63, v154
	v_med3_f32 v12, v13, s63, v154
	v_cvt_pk_fp8_f32 v10, v11, v12
	v_med3_f32 v8, v8, s63, v154
	v_med3_f32 v9, v9, s63, v154
	v_med3_f32 v14, v14, s63, v154
	v_med3_f32 v15, v15, s63, v154
	v_cvt_pk_fp8_f32 v11, v8, v9
	v_cvt_pk_fp8_f32 v10, v14, v15 op_sel:[0,0,1]
	v_mul_f32_e32 v14, 0xb7afc6c0, v36
	v_exp_f32_e32 v14, v14
	v_mul_f32_e32 v15, 0xb7afc6c0, v37
	v_med3_f32 v8, v18, s63, v154
	v_med3_f32 v9, v19, s63, v154
	v_exp_f32_e32 v15, v15
	v_cvt_pk_fp8_f32 v11, v8, v9 op_sel:[0,0,1]
	v_fma_f32 v14, v14, s32, s32
	v_lshl_add_u64 v[250:251], v[250:251], 0, s[68:69]
	v_rcp_f32_e32 v14, v14
	v_fma_f32 v15, v15, s32, s32
	v_rcp_f32_e32 v15, v15
	global_store_dwordx2 v[250:251], v[10:11], off
	v_mul_f32_e32 v11, 0xb7afc6c0, v38
	v_exp_f32_e32 v11, v11
	v_mul_f32_e32 v8, 0xb7afc6c0, v39
	v_exp_f32_e32 v8, v8
	v_mul_f32_e32 v10, v36, v14
	v_mul_f32_e32 v4, v4, v10
	v_mul_f32_e32 v10, v37, v15
	v_mul_f32_e32 v5, v5, v10
	v_fma_f32 v10, v11, s32, s32
	v_cvt_f32_i32_e32 v7, v7
	v_cvt_f32_i32_e32 v6, v6
	v_rcp_f32_e32 v10, v10
	v_fma_f32 v11, v8, s32, s32
	v_mul_f32_e32 v8, 0xb7afc6c0, v32
	v_rcp_f32_e32 v11, v11
	v_exp_f32_e32 v8, v8
	v_mul_f32_e32 v10, v38, v10
	v_mul_f32_e32 v6, v6, v10
	v_mul_f32_e32 v10, v39, v11
	v_fma_f32 v11, v8, s32, s32
	v_rcp_f32_e32 v11, v11
	v_mul_f32_e32 v8, 0xb7afc6c0, v33
	v_exp_f32_e32 v8, v8
	v_mul_f32_e32 v7, v7, v10
	v_mul_f32_e32 v10, v32, v11
	v_mul_f32_e32 v11, 0xb7afc6c0, v34
	v_mul_f32_e32 v0, v0, v10
	v_fma_f32 v10, v8, s32, s32
	v_exp_f32_e32 v11, v11
	v_mul_f32_e32 v8, 0xb7afc6c0, v35
	v_exp_f32_e32 v8, v8
	v_rcp_f32_e32 v10, v10
	v_fma_f32 v11, v11, s32, s32
	v_cvt_f32_i32_e32 v3, v3
	v_cvt_f32_i32_e32 v2, v2
	v_rcp_f32_e32 v11, v11
	v_fma_f32 v8, v8, s32, s32
	v_rcp_f32_e32 v8, v8
	v_mul_f32_e32 v10, v33, v10
	v_mul_f32_e32 v1, v1, v10
	v_mul_f32_e32 v10, v34, v11
	v_mul_f32_e32 v10, v2, v10
	v_mul_f32_e32 v2, v35, v8
	v_mul_f32_e32 v11, v3, v2
	v_med3_f32 v3, v4, s63, v154
	v_med3_f32 v4, v5, s63, v154
	v_cvt_pk_fp8_f32 v2, v3, v4
	v_med3_f32 v0, v0, s63, v154
	v_med3_f32 v1, v1, s63, v154
	v_cvt_pk_fp8_f32 v3, v0, v1
	v_med3_f32 v6, v6, s63, v154
	v_med3_f32 v7, v7, s63, v154
	v_med3_f32 v0, v10, s63, v154
	v_med3_f32 v1, v11, s63, v154
	v_cvt_pk_fp8_f32 v2, v6, v7 op_sel:[0,0,1]
	v_cvt_pk_fp8_f32 v3, v0, v1 op_sel:[0,0,1]
	v_lshl_add_u64 v[0:1], v[250:251], 0, s[68:69]
	s_and_b64 vcc, exec, s[2:3]
	s_mov_b64 s[2:3], -1
	global_store_dwordx2 v[0:1], v[2:3], off
	s_cbranch_vccnz .LBB0_4732
	s_andn2_b64 vcc, exec, s[14:15]
	s_cbranch_vccnz .LBB0_4731
	s_barrier
	s_branch .LBB0_4731
